# hoist combine loads, batch mem K/V staging loads, vmcnt(14) for prefetched K/V LDS writes, G2 bf16 epilogue single load batch
# speedup vs baseline: 1.0138x; 1.0138x over previous
; DI unsigned cvt_pk_bf16(float lo, float hi) { const f32x2_t v = {lo, hi}; const bf16v2_t b = __builtin_convertvector(v, bf16v2_t); return __builtin_bit_cast(unsigned, b); }
; DI float bf_lo(unsigned u) { return __uint_as_float(u << 16); }
; DI float bf_hi(unsigned u) { return __uint_as_float(u & 0xffff0000u); }
;     DI void operator()(const f32x4 (&acc)[2][2][4][2], const Unit& u, int wr, int wc, int fr, int fq) const {
;     ...
; #pragma unroll
;             for (int ai = 0; ai < 2; ++ai) {
;                 u32x4 xv[4][2];
; #pragma unroll
;                 for (int m = 0; m < 4; ++m)
; #pragma unroll
;                     for (int bj = 0; bj < 2; ++bj) xv[m][bj] = *(const u32x4*)(Xb + (size_t)(row0 + ai * HALF + m * 16) * 1024 + col0 + bj * HALF);
; #pragma unroll
;                 for (int m = 0; m < 4; ++m) { const size_t ro = (size_t)(row0 + ai * HALF + m * 16) * 1024 + col0;
; #pragma unroll
;                     for (int bj = 0; bj < 2; ++bj) {
;                         const u32x4 x = xv[m][bj];
;                         const f32x4 x0 = (f32x4){bf_lo(x.x), bf_hi(x.x), bf_lo(x.y), bf_hi(x.y)}, x1 = (f32x4){bf_lo(x.z), bf_hi(x.z), bf_lo(x.w), bf_hi(x.w)};
;                         const f32x4 y0 = acc[ai][bj][m][0] + x0, y1 = acc[ai][bj][m][1] + x1;
;                         u32x4 w; w.x = cvt_pk_bf16(y0[0], y0[1]); w.y = cvt_pk_bf16(y0[2], y0[3]); w.z = cvt_pk_bf16(y1[0], y1[1]); w.w = cvt_pk_bf16(y1[2], y1[3]);
;                         *(u32x4*)(Y + ro + bj * HALF) = w;
;                     }
;                 }
;             }
.LBB0_86:
	v_readlane_b32 s72, v254, 58
	v_readlane_b32 s73, v254, 59
	s_andn2_b64 vcc, exec, s[22:23]
	s_cbranch_vccnz .LBB0_74
	v_lshl_add_u64 v[182:183], s[26:27], 0, v[174:175]
	v_lshl_add_u64 v[134:135], v[182:183], 0, v[176:177]
	global_load_dwordx4 v[158:161], v[134:135], off
	global_load_dwordx4 v[190:193], v[134:135], off offset:256
	v_ashrrev_i32_e32 v145, 31, v144
	v_lshlrev_b64 v[186:187], 11, v[144:145]
	v_lshl_add_u64 v[134:135], v[182:183], 0, v[186:187]
	global_load_dwordx4 v[194:197], v[134:135], off
	global_load_dwordx4 v[150:153], v[134:135], off offset:256
	v_ashrrev_i32_e32 v143, 31, v142
	v_lshlrev_b64 v[184:185], 11, v[142:143]
	v_lshl_add_u64 v[134:135], v[182:183], 0, v[184:185]
	global_load_dwordx4 v[146:149], v[134:135], off
	global_load_dwordx4 v[142:145], v[134:135], off offset:256
	v_ashrrev_i32_e32 v181, 31, v180
	v_lshlrev_b64 v[180:181], 11, v[180:181]
	v_lshl_add_u64 v[134:135], v[182:183], 0, v[180:181]
	global_load_dwordx4 v[138:141], v[134:135], off
	s_nop 0
	global_load_dwordx4 v[134:137], v[134:135], off offset:256
	s_mov_b64 s[22:23], 0x40000
	s_mov_b64 vcc, 0x40000
	v_lshl_add_u64 v[246:247], v[176:177], 0, vcc
	v_lshl_add_u64 v[246:247], v[182:183], 0, v[246:247]
	global_load_dwordx4 v[202:205], v[246:247], off
	global_load_dwordx4 v[206:209], v[246:247], off offset:256
	s_mov_b64 vcc, 0x48000
	v_lshl_add_u64 v[246:247], v[176:177], 0, vcc
	v_lshl_add_u64 v[246:247], v[182:183], 0, v[246:247]
	global_load_dwordx4 v[210:213], v[246:247], off
	global_load_dwordx4 v[214:217], v[246:247], off offset:256
	s_mov_b64 vcc, 0x50000
	v_lshl_add_u64 v[246:247], v[176:177], 0, vcc
	v_lshl_add_u64 v[246:247], v[182:183], 0, v[246:247]
	global_load_dwordx4 v[218:221], v[246:247], off
	global_load_dwordx4 v[222:225], v[246:247], off offset:256
	s_mov_b64 vcc, 0x58000
	v_lshl_add_u64 v[246:247], v[176:177], 0, vcc
	v_lshl_add_u64 v[246:247], v[182:183], 0, v[246:247]
	global_load_dwordx4 v[226:229], v[246:247], off
	global_load_dwordx4 v[242:245], v[246:247], off offset:256
	s_waitcnt vmcnt(0)
	v_lshlrev_b32_e32 v198, 16, v158
	v_and_b32_e32 v199, 0xffff0000, v158
	v_lshlrev_b32_e32 v158, 16, v159
	v_and_b32_e32 v159, 0xffff0000, v159
	v_lshlrev_b32_e32 v200, 16, v160
	v_and_b32_e32 v201, 0xffff0000, v160
	v_lshlrev_b32_e32 v160, 16, v161
	v_and_b32_e32 v161, 0xffff0000, v161
	v_pk_add_f32 v[132:133], v[132:133], v[158:159]
	v_pk_add_f32 v[130:131], v[130:131], v[198:199]
	v_pk_add_f32 v[158:159], v[128:129], v[160:161]
	v_pk_add_f32 v[128:129], v[126:127], v[200:201]
	v_cvt_pk_bf16_f32 v126, v130, v131
	v_cvt_pk_bf16_f32 v127, v132, v133
	v_cvt_pk_bf16_f32 v128, v128, v129
	v_cvt_pk_bf16_f32 v129, v158, v159
	v_lshl_add_u64 v[130:131], v[178:179], 0, v[174:175]
	global_store_dwordx4 v[130:131], v[126:129], off
	v_lshlrev_b32_e32 v132, 16, v192
	v_and_b32_e32 v133, 0xffff0000, v192
	v_lshlrev_b32_e32 v126, 16, v190
	v_and_b32_e32 v127, 0xffff0000, v190
	v_lshlrev_b32_e32 v128, 16, v191
	v_and_b32_e32 v129, 0xffff0000, v191
	v_lshlrev_b32_e32 v158, 16, v193
	v_and_b32_e32 v159, 0xffff0000, v193
	v_pk_add_f32 v[116:117], v[116:117], v[128:129]
	v_pk_add_f32 v[114:115], v[114:115], v[126:127]
	v_pk_add_f32 v[126:127], v[112:113], v[158:159]
	v_pk_add_f32 v[112:113], v[110:111], v[132:133]
	v_cvt_pk_bf16_f32 v110, v114, v115
	v_cvt_pk_bf16_f32 v111, v116, v117
	v_cvt_pk_bf16_f32 v112, v112, v113
	v_cvt_pk_bf16_f32 v113, v126, v127
	global_store_dwordx4 v[130:131], v[110:113], off offset:256
	v_lshlrev_b32_e32 v114, 16, v196
	v_and_b32_e32 v115, 0xffff0000, v196
	v_lshlrev_b32_e32 v110, 16, v194
	v_and_b32_e32 v111, 0xffff0000, v194
	v_lshlrev_b32_e32 v112, 16, v195
	v_and_b32_e32 v113, 0xffff0000, v195
	v_lshlrev_b32_e32 v116, 16, v197
	v_and_b32_e32 v117, 0xffff0000, v197
	v_pk_add_f32 v[112:113], v[124:125], v[112:113]
	v_pk_add_f32 v[110:111], v[122:123], v[110:111]
	v_pk_add_f32 v[114:115], v[118:119], v[114:115]
	v_pk_add_f32 v[116:117], v[120:121], v[116:117]
	v_cvt_pk_bf16_f32 v110, v110, v111
	v_cvt_pk_bf16_f32 v111, v112, v113
	v_cvt_pk_bf16_f32 v112, v114, v115
	v_lshl_add_u64 v[114:115], s[26:27], 0, v[186:187]
	v_cvt_pk_bf16_f32 v113, v116, v117
	v_lshl_add_u64 v[114:115], v[114:115], 0, v[174:175]
	global_store_dwordx4 v[114:115], v[110:113], off
	v_lshlrev_b32_e32 v116, 16, v152
	v_and_b32_e32 v117, 0xffff0000, v152
	v_lshlrev_b32_e32 v110, 16, v150
	v_and_b32_e32 v111, 0xffff0000, v150
	v_lshlrev_b32_e32 v112, 16, v151
	v_and_b32_e32 v113, 0xffff0000, v151
	v_lshlrev_b32_e32 v118, 16, v153
	v_and_b32_e32 v119, 0xffff0000, v153
	v_pk_add_f32 v[108:109], v[108:109], v[112:113]
	v_pk_add_f32 v[106:107], v[106:107], v[110:111]
	v_pk_add_f32 v[110:111], v[104:105], v[118:119]
	v_pk_add_f32 v[104:105], v[102:103], v[116:117]
	v_cvt_pk_bf16_f32 v102, v106, v107
	v_cvt_pk_bf16_f32 v103, v108, v109
	v_cvt_pk_bf16_f32 v104, v104, v105
	v_cvt_pk_bf16_f32 v105, v110, v111
	global_store_dwordx4 v[114:115], v[102:105], off offset:256
	v_lshlrev_b32_e32 v106, 16, v148
	v_and_b32_e32 v107, 0xffff0000, v148
	v_lshlrev_b32_e32 v102, 16, v146
	v_and_b32_e32 v103, 0xffff0000, v146
	v_lshlrev_b32_e32 v104, 16, v147
	v_and_b32_e32 v105, 0xffff0000, v147
	v_lshlrev_b32_e32 v108, 16, v149
	v_and_b32_e32 v109, 0xffff0000, v149
	v_pk_add_f32 v[98:99], v[98:99], v[102:103]
	v_pk_add_f32 v[100:101], v[100:101], v[104:105]
	v_pk_add_f32 v[102:103], v[96:97], v[108:109]
	v_pk_add_f32 v[96:97], v[94:95], v[106:107]
	v_cvt_pk_bf16_f32 v94, v98, v99
	v_lshl_add_u64 v[98:99], s[26:27], 0, v[184:185]
	v_cvt_pk_bf16_f32 v95, v100, v101
	v_cvt_pk_bf16_f32 v96, v96, v97
	v_cvt_pk_bf16_f32 v97, v102, v103
	v_lshl_add_u64 v[98:99], v[98:99], 0, v[174:175]
; DI unsigned cvt_pk_bf16(float lo, float hi) { const f32x2_t v = {lo, hi}; const bf16v2_t b = __builtin_convertvector(v, bf16v2_t); return __builtin_bit_cast(unsigned, b); }
; DI float bf_lo(unsigned u) { return __uint_as_float(u << 16); }
; DI float bf_hi(unsigned u) { return __uint_as_float(u & 0xffff0000u); }
;     DI void operator()(const f32x4 (&acc)[2][2][4][2], const Unit& u, int wr, int wc, int fr, int fq) const {
;     ...
;                 for (int m = 0; m < 4; ++m) { const size_t ro = (size_t)(row0 + ai * HALF + m * 16) * 1024 + col0;
; #pragma unroll
;                     for (int bj = 0; bj < 2; ++bj) {
;                         const u32x4 x = xv[m][bj];
;                         const f32x4 x0 = (f32x4){bf_lo(x.x), bf_hi(x.x), bf_lo(x.y), bf_hi(x.y)}, x1 = (f32x4){bf_lo(x.z), bf_hi(x.z), bf_lo(x.w), bf_hi(x.w)};
;                         const f32x4 y0 = acc[ai][bj][m][0] + x0, y1 = acc[ai][bj][m][1] + x1;
;                         u32x4 w; w.x = cvt_pk_bf16(y0[0], y0[1]); w.y = cvt_pk_bf16(y0[2], y0[3]); w.z = cvt_pk_bf16(y1[0], y1[1]); w.w = cvt_pk_bf16(y1[2], y1[3]);
;                         *(u32x4*)(Y + ro + bj * HALF) = w;
;                     }
	global_store_dwordx4 v[98:99], v[94:97], off
	v_lshlrev_b32_e32 v100, 16, v144
	v_and_b32_e32 v101, 0xffff0000, v144
	v_lshlrev_b32_e32 v94, 16, v142
	v_and_b32_e32 v95, 0xffff0000, v142
	v_lshlrev_b32_e32 v96, 16, v143
	v_and_b32_e32 v97, 0xffff0000, v143
	v_lshlrev_b32_e32 v102, 16, v145
	v_and_b32_e32 v103, 0xffff0000, v145
	v_pk_add_f32 v[92:93], v[92:93], v[96:97]
	v_pk_add_f32 v[90:91], v[90:91], v[94:95]
	v_pk_add_f32 v[94:95], v[88:89], v[102:103]
	v_pk_add_f32 v[88:89], v[86:87], v[100:101]
	v_cvt_pk_bf16_f32 v86, v90, v91
	v_cvt_pk_bf16_f32 v87, v92, v93
	v_cvt_pk_bf16_f32 v88, v88, v89
	v_cvt_pk_bf16_f32 v89, v94, v95
	global_store_dwordx4 v[98:99], v[86:89], off offset:256
	v_lshlrev_b32_e32 v90, 16, v140
	v_and_b32_e32 v91, 0xffff0000, v140
	v_lshlrev_b32_e32 v86, 16, v138
	v_and_b32_e32 v87, 0xffff0000, v138
	v_lshlrev_b32_e32 v88, 16, v139
	v_and_b32_e32 v89, 0xffff0000, v139
	v_lshlrev_b32_e32 v92, 16, v141
	v_and_b32_e32 v93, 0xffff0000, v141
	v_pk_add_f32 v[82:83], v[82:83], v[86:87]
	v_pk_add_f32 v[84:85], v[84:85], v[88:89]
	v_pk_add_f32 v[86:87], v[80:81], v[92:93]
	v_pk_add_f32 v[80:81], v[78:79], v[90:91]
	v_cvt_pk_bf16_f32 v78, v82, v83
	v_lshl_add_u64 v[82:83], s[26:27], 0, v[180:181]
	v_cvt_pk_bf16_f32 v79, v84, v85
	v_cvt_pk_bf16_f32 v80, v80, v81
	v_cvt_pk_bf16_f32 v81, v86, v87
	v_lshl_add_u64 v[82:83], v[82:83], 0, v[174:175]
	global_store_dwordx4 v[82:83], v[78:81], off
	v_lshlrev_b32_e32 v84, 16, v136
	v_and_b32_e32 v85, 0xffff0000, v136
	v_lshlrev_b32_e32 v78, 16, v134
	v_and_b32_e32 v79, 0xffff0000, v134
	v_lshlrev_b32_e32 v80, 16, v135
	v_and_b32_e32 v81, 0xffff0000, v135
	v_lshlrev_b32_e32 v86, 16, v137
	v_and_b32_e32 v87, 0xffff0000, v137
	v_pk_add_f32 v[76:77], v[76:77], v[80:81]
	v_pk_add_f32 v[74:75], v[74:75], v[78:79]
	v_pk_add_f32 v[78:79], v[72:73], v[86:87]
	v_pk_add_f32 v[72:73], v[70:71], v[84:85]
	v_cvt_pk_bf16_f32 v70, v74, v75
	v_cvt_pk_bf16_f32 v71, v76, v77
	v_cvt_pk_bf16_f32 v72, v72, v73
	v_cvt_pk_bf16_f32 v73, v78, v79
	v_lshl_add_u64 v[102:103], v[176:177], 0, s[22:23]
	global_store_dwordx4 v[82:83], v[70:73], off offset:256
	s_mov_b64 s[22:23], 0x48000
	v_lshl_add_u64 v[104:105], v[176:177], 0, s[22:23]
	s_mov_b64 s[22:23], 0x50000
	v_lshl_add_u64 v[106:107], v[176:177], 0, s[22:23]
	s_mov_b64 s[22:23], 0x58000
	v_lshl_add_u64 v[146:147], v[176:177], 0, s[22:23]
	v_lshlrev_b32_e32 v108, 16, v202
	v_and_b32_e32 v109, 0xffff0000, v202
	v_lshlrev_b32_e32 v202, 16, v203
	v_and_b32_e32 v203, 0xffff0000, v203
	v_lshlrev_b32_e32 v110, 16, v204
	v_and_b32_e32 v111, 0xffff0000, v204
	v_lshlrev_b32_e32 v204, 16, v205
	v_and_b32_e32 v205, 0xffff0000, v205
	v_pk_add_f32 v[66:67], v[66:67], v[108:109]
	v_pk_add_f32 v[68:69], v[68:69], v[202:203]
	v_pk_add_f32 v[202:203], v[64:65], v[204:205]
	v_pk_add_f32 v[64:65], v[62:63], v[110:111]
	v_cvt_pk_bf16_f32 v62, v66, v67
	v_lshl_add_u64 v[66:67], s[26:27], 0, v[102:103]
	v_cvt_pk_bf16_f32 v63, v68, v69
	v_cvt_pk_bf16_f32 v64, v64, v65
	v_cvt_pk_bf16_f32 v65, v202, v203
	v_lshl_add_u64 v[66:67], v[66:67], 0, v[174:175]
	global_store_dwordx4 v[66:67], v[62:65], off
	v_lshlrev_b32_e32 v68, 16, v208
	v_and_b32_e32 v69, 0xffff0000, v208
	v_lshlrev_b32_e32 v62, 16, v206
	v_and_b32_e32 v63, 0xffff0000, v206
	v_lshlrev_b32_e32 v64, 16, v207
	v_and_b32_e32 v65, 0xffff0000, v207
	v_lshlrev_b32_e32 v202, 16, v209
	v_and_b32_e32 v203, 0xffff0000, v209
	v_pk_add_f32 v[60:61], v[60:61], v[64:65]
	v_pk_add_f32 v[58:59], v[58:59], v[62:63]
	v_pk_add_f32 v[62:63], v[52:53], v[202:203]
	v_pk_add_f32 v[52:53], v[50:51], v[68:69]
	v_cvt_pk_bf16_f32 v50, v58, v59
	v_cvt_pk_bf16_f32 v51, v60, v61
	v_cvt_pk_bf16_f32 v52, v52, v53
	v_cvt_pk_bf16_f32 v53, v62, v63
	global_store_dwordx4 v[66:67], v[50:53], off offset:256
; DI unsigned cvt_pk_bf16(float lo, float hi) { const f32x2_t v = {lo, hi}; const bf16v2_t b = __builtin_convertvector(v, bf16v2_t); return __builtin_bit_cast(unsigned, b); }
; DI float bf_lo(unsigned u) { return __uint_as_float(u << 16); }
; DI float bf_hi(unsigned u) { return __uint_as_float(u & 0xffff0000u); }
;     DI void operator()(const f32x4 (&acc)[2][2][4][2], const Unit& u, int wr, int wc, int fr, int fq) const {
;     ...
;                 for (int m = 0; m < 4; ++m) { const size_t ro = (size_t)(row0 + ai * HALF + m * 16) * 1024 + col0;
; #pragma unroll
;                     for (int bj = 0; bj < 2; ++bj) {
;                         const u32x4 x = xv[m][bj];
;                         const f32x4 x0 = (f32x4){bf_lo(x.x), bf_hi(x.x), bf_lo(x.y), bf_hi(x.y)}, x1 = (f32x4){bf_lo(x.z), bf_hi(x.z), bf_lo(x.w), bf_hi(x.w)};
;                         const f32x4 y0 = acc[ai][bj][m][0] + x0, y1 = acc[ai][bj][m][1] + x1;
;                         u32x4 w; w.x = cvt_pk_bf16(y0[0], y0[1]); w.y = cvt_pk_bf16(y0[2], y0[3]); w.z = cvt_pk_bf16(y1[0], y1[1]); w.w = cvt_pk_bf16(y1[2], y1[3]);
;                         *(u32x4*)(Y + ro + bj * HALF) = w;
;                     }
	v_lshlrev_b32_e32 v58, 16, v212
	v_and_b32_e32 v59, 0xffff0000, v212
	v_lshlrev_b32_e32 v50, 16, v210
	v_and_b32_e32 v51, 0xffff0000, v210
	v_lshlrev_b32_e32 v52, 16, v211
	v_and_b32_e32 v53, 0xffff0000, v211
	v_lshlrev_b32_e32 v60, 16, v213
	v_and_b32_e32 v61, 0xffff0000, v213
	v_pk_add_f32 v[50:51], v[54:55], v[50:51]
	v_pk_add_f32 v[52:53], v[56:57], v[52:53]
	v_pk_add_f32 v[54:55], v[48:49], v[60:61]
	v_pk_add_f32 v[48:49], v[46:47], v[58:59]
	v_cvt_pk_bf16_f32 v46, v50, v51
	v_lshl_add_u64 v[50:51], s[26:27], 0, v[104:105]
	v_cvt_pk_bf16_f32 v47, v52, v53
	v_cvt_pk_bf16_f32 v48, v48, v49
	v_cvt_pk_bf16_f32 v49, v54, v55
	v_lshl_add_u64 v[50:51], v[50:51], 0, v[174:175]
	global_store_dwordx4 v[50:51], v[46:49], off
	v_lshlrev_b32_e32 v52, 16, v216
	v_and_b32_e32 v53, 0xffff0000, v216
	v_lshlrev_b32_e32 v46, 16, v214
	v_and_b32_e32 v47, 0xffff0000, v214
	v_lshlrev_b32_e32 v48, 16, v215
	v_and_b32_e32 v49, 0xffff0000, v215
	v_lshlrev_b32_e32 v54, 16, v217
	v_and_b32_e32 v55, 0xffff0000, v217
	v_pk_add_f32 v[44:45], v[44:45], v[48:49]
	v_pk_add_f32 v[42:43], v[42:43], v[46:47]
	v_pk_add_f32 v[46:47], v[36:37], v[54:55]
	v_pk_add_f32 v[36:37], v[34:35], v[52:53]
	v_cvt_pk_bf16_f32 v34, v42, v43
	v_cvt_pk_bf16_f32 v35, v44, v45
	v_cvt_pk_bf16_f32 v36, v36, v37
	v_cvt_pk_bf16_f32 v37, v46, v47
	global_store_dwordx4 v[50:51], v[34:37], off offset:256
	v_lshlrev_b32_e32 v42, 16, v220
	v_and_b32_e32 v43, 0xffff0000, v220
	v_lshlrev_b32_e32 v34, 16, v218
	v_and_b32_e32 v35, 0xffff0000, v218
	v_lshlrev_b32_e32 v36, 16, v219
	v_and_b32_e32 v37, 0xffff0000, v219
	v_lshlrev_b32_e32 v44, 16, v221
	v_and_b32_e32 v45, 0xffff0000, v221
	v_pk_add_f32 v[34:35], v[38:39], v[34:35]
	v_pk_add_f32 v[36:37], v[40:41], v[36:37]
	v_pk_add_f32 v[38:39], v[28:29], v[44:45]
	v_pk_add_f32 v[28:29], v[26:27], v[42:43]
	v_cvt_pk_bf16_f32 v26, v34, v35
	v_lshl_add_u64 v[34:35], s[26:27], 0, v[106:107]
	v_cvt_pk_bf16_f32 v27, v36, v37
	v_cvt_pk_bf16_f32 v28, v28, v29
	v_cvt_pk_bf16_f32 v29, v38, v39
	v_lshl_add_u64 v[34:35], v[34:35], 0, v[174:175]
	global_store_dwordx4 v[34:35], v[26:29], off
	v_lshlrev_b32_e32 v36, 16, v224
	v_and_b32_e32 v37, 0xffff0000, v224
	v_lshlrev_b32_e32 v26, 16, v222
	v_and_b32_e32 v27, 0xffff0000, v222
	v_lshlrev_b32_e32 v28, 16, v223
	v_and_b32_e32 v29, 0xffff0000, v223
	v_lshlrev_b32_e32 v38, 16, v225
	v_and_b32_e32 v39, 0xffff0000, v225
	v_pk_add_f32 v[24:25], v[24:25], v[28:29]
	v_pk_add_f32 v[22:23], v[22:23], v[26:27]
	v_pk_add_f32 v[26:27], v[16:17], v[38:39]
	v_pk_add_f32 v[16:17], v[14:15], v[36:37]
	v_cvt_pk_bf16_f32 v14, v22, v23
	v_cvt_pk_bf16_f32 v15, v24, v25
	v_cvt_pk_bf16_f32 v16, v16, v17
	v_cvt_pk_bf16_f32 v17, v26, v27
	global_store_dwordx4 v[34:35], v[14:17], off offset:256
	v_lshlrev_b32_e32 v22, 16, v228
	v_and_b32_e32 v23, 0xffff0000, v228
	v_lshlrev_b32_e32 v14, 16, v226
	v_and_b32_e32 v15, 0xffff0000, v226
	v_lshlrev_b32_e32 v16, 16, v227
	v_and_b32_e32 v17, 0xffff0000, v227
	v_lshlrev_b32_e32 v24, 16, v229
	v_and_b32_e32 v25, 0xffff0000, v229
	v_pk_add_f32 v[14:15], v[18:19], v[14:15]
	v_pk_add_f32 v[16:17], v[20:21], v[16:17]
	v_pk_add_f32 v[18:19], v[10:11], v[24:25]
	v_pk_add_f32 v[10:11], v[8:9], v[22:23]
	v_cvt_pk_bf16_f32 v8, v14, v15
	v_lshl_add_u64 v[14:15], s[26:27], 0, v[146:147]
	v_cvt_pk_bf16_f32 v9, v16, v17
	v_cvt_pk_bf16_f32 v10, v10, v11
	v_cvt_pk_bf16_f32 v11, v18, v19
	v_lshl_add_u64 v[14:15], v[14:15], 0, v[174:175]
	v_lshlrev_b32_e32 v134, 16, v242
	v_and_b32_e32 v135, 0xffff0000, v242
	v_lshlrev_b32_e32 v136, 16, v243
	v_and_b32_e32 v137, 0xffff0000, v243
	v_lshlrev_b32_e32 v138, 16, v244
	v_and_b32_e32 v139, 0xffff0000, v244
	v_lshlrev_b32_e32 v140, 16, v245
	v_and_b32_e32 v141, 0xffff0000, v245
	global_store_dwordx4 v[14:15], v[8:11], off
	s_branch .LBB0_74

; DI void dil_combine(const bf16_t* og, const float* lse, const bf16_t* proj, bf16_t* br, int b0, int u0, int u1, int ustride) {
;     for (int u = u0; u < u1; u += ustride) {
;         const int row = u / 96, ch = u - row * 96, head = ch >> 4;
;         const float l0 = lse[(size_t)row * 18 + head], l1 = lse[(size_t)row * 18 + 6 + head], l2 = lse[(size_t)row * 18 + 12 + head];
;         const float m = fmaxf(l0, fmaxf(l1, l2));
;         float e0 = __expf(l0 - m), e1 = __expf(l1 - m), e2 = __expf(l2 - m);
;         const float is = 1.0f / (e0 + e1 + e2); e0 *= is; e1 *= is; e2 *= is;
;         const bf16_t* ob = og + (size_t)row * 2304 + ch * 8;
;         const u32x4 a = *(const u32x4*)ob, bq = *(const u32x4*)(ob + 768), c = *(const u32x4*)(ob + 1536);
;         const u32x4 gv = *(const u32x4*)(proj + (size_t)row * DIL_N + DB_GATE + ch * 8);
.LBB0_132:
	v_mul_hi_i32 v1, v2, s17
	v_lshrrev_b32_e32 v3, 31, v1
	v_ashrrev_i32_e32 v1, 4, v1
	v_add_u32_e32 v4, v1, v3
	s_waitcnt lgkmcnt(0)
	v_mad_u64_u32 v[6:7], s[22:23], v4, s38, v[2:3]
	v_ashrrev_i32_e32 v6, 4, v6
	v_mov_b64_e32 v[8:9], s[48:49]
	v_ashrrev_i32_e32 v7, 31, v6
	v_mad_i64_i32 v[8:9], s[22:23], v4, s39, v[8:9]
	v_lshl_add_u64 v[6:7], v[6:7], 2, v[8:9]
	global_load_dword v1, v[6:7], off
	global_load_dword v3, v[6:7], off offset:24
	s_nop 0
	global_load_dword v6, v[6:7], off offset:48
	v_ashrrev_i32_e32 v5, 31, v4
	v_lshlrev_b64 v[22:23], 14, v[4:5]
	v_lshl_add_u64 v[22:23], s[42:43], 0, v[22:23]
	v_add_u32_e32 v2, s15, v2
	s_mov_b32 s0, 0x17ffff
	v_mad_u64_u32 v[10:11], s[22:23], v4, s35, v[0:1]
	v_ashrrev_i32_e32 v11, 31, v10
	v_lshlrev_b64 v[30:31], 1, v[10:11]
	v_mov_b64_e32 v[8:9], s[46:47]
	v_lshl_add_u64 v[22:23], v[22:23], 0, v[30:31]
	v_mad_i64_i32 v[8:9], s[22:23], v4, s40, v[8:9]
	v_add_co_u32_e32 v22, vcc, s34, v22
	v_lshl_add_u64 v[18:19], v[8:9], 0, v[30:31]
	s_nop 0
	v_addc_co_u32_e32 v23, vcc, 0, v23, vcc
	global_load_dwordx4 v[8:11], v[18:19], off
	global_load_dwordx4 v[14:17], v[18:19], off offset:1536
	s_nop 0
	global_load_dwordx4 v[18:21], v[18:19], off offset:3072
	global_load_dwordx4 v[22:25], v[22:23], off offset:2048
	s_waitcnt vmcnt(4)
	v_max3_f32 v7, v1, v3, v6
	v_sub_f32_e32 v1, v1, v7
	v_mul_f32_e32 v1, 0x3fb8aa3b, v1
	v_exp_f32_e32 v27, v1
	v_sub_f32_e32 v1, v3, v7
	v_mul_f32_e32 v1, 0x3fb8aa3b, v1
	v_exp_f32_e32 v26, v1
	v_sub_f32_e32 v1, v6, v7
	v_mul_f32_e32 v1, 0x3fb8aa3b, v1
	v_exp_f32_e32 v1, v1
	v_add_f32_e32 v3, v27, v26
	v_add_f32_e32 v3, v1, v3
	v_div_scale_f32 v6, s[22:23], v3, v3, 1.0
	v_rcp_f32_e32 v7, v6
	s_nop 0
	v_fma_f32 v34, -v6, v7, 1.0
	v_fmac_f32_e32 v7, v34, v7
	v_div_scale_f32 v34, vcc, 1.0, v3, 1.0
	v_mul_f32_e32 v35, v34, v7
	v_fma_f32 v36, -v6, v35, v34
	v_fmac_f32_e32 v35, v36, v7
	v_fma_f32 v6, -v6, v35, v34
	s_nop 1
	v_div_fmas_f32 v6, v6, v7, v35
	v_div_fixup_f32 v28, v6, v3, 1.0
	v_mul_f32_e32 v6, v1, v28
	v_pk_mul_f32 v[26:27], v[26:27], v[28:29] op_sel_hi:[1,0]
	v_lshlrev_b64 v[4:5], 11, v[4:5]
	v_lshl_add_u64 v[4:5], s[30:31], 0, v[4:5]
	v_lshl_add_u64 v[4:5], v[4:5], 0, v[30:31]
	v_add_u32_e32 v0, s19, v0
	s_waitcnt vmcnt(0)
	v_and_b32_e32 v29, 0xffff0000, v8
	v_lshlrev_b32_e32 v34, 16, v8
	v_lshlrev_b32_e32 v28, 16, v14
	v_and_b32_e32 v35, 0xffff0000, v14
	v_lshlrev_b32_e32 v1, 16, v22
	v_and_b32_e32 v3, 0xffff0000, v22
	v_mul_f32_e32 v7, 0xbfb8aa3b, v1
	v_exp_f32_e32 v38, v7
	v_mul_f32_e32 v7, 0xbfb8aa3b, v3
	s_waitcnt lgkmcnt(0)
; DI unsigned cvt_pk_bf16(float lo, float hi) { const f32x2_t v = {lo, hi}; const bf16v2_t b = __builtin_convertvector(v, bf16v2_t); return __builtin_bit_cast(unsigned, b); }
; DI float bf_lo(unsigned u) { return __uint_as_float(u << 16); }
; DI float bf_hi(unsigned u) { return __uint_as_float(u & 0xffff0000u); }
; DI float silu_f(float x) { return x / (1.0f + __expf(-x)); }
; DI void dil_combine(const bf16_t* og, const float* lse, const bf16_t* proj, bf16_t* br, int b0, int u0, int u1, int ustride) {
;     ...
;         u32x4 w;
; #pragma unroll
;         for (int e = 0; e < 4; ++e) {
;             const float vlo = e0 * bf_lo(a[e]) + e1 * bf_lo(bq[e]) + e2 * bf_lo(c[e]);
;             const float vhi = e0 * bf_hi(a[e]) + e1 * bf_hi(bq[e]) + e2 * bf_hi(c[e]);
;             w[e] = cvt_pk_bf16(vlo * silu_f(bf_lo(gv[e])), vhi * silu_f(bf_hi(gv[e])));
;         }
;         *(u32x4*)(br + ((size_t)b0 * SEQ + row) * 1024 + ch * 8) = w;
	v_exp_f32_e32 v39, v7
	v_lshlrev_b32_e32 v36, 16, v18
	v_and_b32_e32 v37, 0xffff0000, v18
	v_pk_mul_f32 v[34:35], v[26:27], v[34:35] op_sel:[1,0] op_sel_hi:[0,1]
	v_pk_add_f32 v[38:39], v[38:39], 1.0 op_sel_hi:[1,0]
	v_pk_fma_f32 v[28:29], v[26:27], v[28:29], v[34:35]
	v_div_scale_f32 v7, s[22:23], v39, v39, v3
	v_rcp_f32_e32 v8, v7
	s_nop 0
	v_fma_f32 v13, -v7, v8, 1.0
	v_fmac_f32_e32 v8, v13, v8
	v_div_scale_f32 v13, vcc, v3, v39, v3
	v_mul_f32_e32 v14, v13, v8
	v_fma_f32 v18, -v7, v14, v13
	v_fmac_f32_e32 v14, v18, v8
	v_fma_f32 v7, -v7, v14, v13
	v_div_fmas_f32 v7, v7, v8, v14
	v_div_fixup_f32 v39, v7, v39, v3
	v_div_scale_f32 v3, s[22:23], v38, v38, v1
	v_rcp_f32_e32 v7, v3
	v_lshlrev_b32_e32 v18, 16, v19
	v_and_b32_e32 v19, 0xffff0000, v19
	v_fma_f32 v8, -v3, v7, 1.0
	v_fmac_f32_e32 v7, v8, v7
	v_div_scale_f32 v8, vcc, v1, v38, v1
	v_mul_f32_e32 v13, v8, v7
	v_fma_f32 v14, -v3, v13, v8
	v_fmac_f32_e32 v13, v14, v7
	v_fma_f32 v3, -v3, v13, v8
	v_div_fmas_f32 v3, v3, v7, v13
	v_div_fixup_f32 v38, v3, v38, v1
	v_lshlrev_b32_e32 v1, 16, v23
	v_pk_fma_f32 v[28:29], v[6:7], v[36:37], v[28:29] op_sel_hi:[0,1,1]
	v_and_b32_e32 v3, 0xffff0000, v23
	v_mul_f32_e32 v7, 0xbfb8aa3b, v1
	v_exp_f32_e32 v22, v7
	v_mul_f32_e32 v7, 0xbfb8aa3b, v3
	v_exp_f32_e32 v23, v7
	v_pk_mul_f32 v[28:29], v[38:39], v[28:29]
	v_lshlrev_b32_e32 v14, 16, v9
	v_cvt_pk_bf16_f32 v8, v28, v29
	v_pk_add_f32 v[22:23], v[22:23], 1.0 op_sel_hi:[1,0]
	v_and_b32_e32 v29, 0xffff0000, v9
	v_div_scale_f32 v7, s[22:23], v23, v23, v3
	v_rcp_f32_e32 v9, v7
	v_lshlrev_b32_e32 v28, 16, v15
	v_and_b32_e32 v15, 0xffff0000, v15
	v_pk_mul_f32 v[14:15], v[26:27], v[14:15] op_sel:[1,0] op_sel_hi:[0,1]
	v_fma_f32 v13, -v7, v9, 1.0
	v_fmac_f32_e32 v9, v13, v9
	v_div_scale_f32 v13, vcc, v3, v23, v3
	v_mul_f32_e32 v33, v13, v9
	v_fma_f32 v34, -v7, v33, v13
	v_fmac_f32_e32 v33, v34, v9
	v_fma_f32 v7, -v7, v33, v13
	v_div_fmas_f32 v7, v7, v9, v33
	v_div_fixup_f32 v23, v7, v23, v3
	v_div_scale_f32 v3, s[22:23], v22, v22, v1
	v_rcp_f32_e32 v7, v3
	v_pk_fma_f32 v[14:15], v[26:27], v[28:29], v[14:15]
	v_fma_f32 v9, -v3, v7, 1.0
	v_fmac_f32_e32 v7, v9, v7
	v_div_scale_f32 v9, vcc, v1, v22, v1
	v_mul_f32_e32 v13, v9, v7
	v_fma_f32 v33, -v3, v13, v9
	v_fmac_f32_e32 v13, v33, v7
	v_fma_f32 v3, -v3, v13, v9
	v_div_fmas_f32 v3, v3, v7, v13
	v_div_fixup_f32 v22, v3, v22, v1
	v_lshlrev_b32_e32 v1, 16, v24
	v_pk_fma_f32 v[14:15], v[6:7], v[18:19], v[14:15] op_sel_hi:[0,1,1]
	v_and_b32_e32 v3, 0xffff0000, v24
	v_mul_f32_e32 v7, 0xbfb8aa3b, v1
	v_exp_f32_e32 v28, v7
	v_mul_f32_e32 v7, 0xbfb8aa3b, v3
	v_exp_f32_e32 v29, v7
	v_pk_mul_f32 v[14:15], v[22:23], v[14:15]
	v_lshlrev_b32_e32 v18, 16, v10
	v_cvt_pk_bf16_f32 v9, v14, v15
	v_pk_add_f32 v[28:29], v[28:29], 1.0 op_sel_hi:[1,0]
	v_and_b32_e32 v15, 0xffff0000, v10
	v_div_scale_f32 v7, s[22:23], v29, v29, v3
	v_rcp_f32_e32 v10, v7
	v_lshlrev_b32_e32 v14, 16, v16
	v_and_b32_e32 v19, 0xffff0000, v16
	v_lshlrev_b32_e32 v22, 16, v20
	v_fma_f32 v13, -v7, v10, 1.0
	v_fmac_f32_e32 v10, v13, v10
	v_div_scale_f32 v13, vcc, v3, v29, v3
	v_mul_f32_e32 v16, v13, v10
	v_and_b32_e32 v23, 0xffff0000, v20
	v_fma_f32 v20, -v7, v16, v13
	v_fmac_f32_e32 v16, v20, v10
	v_fma_f32 v7, -v7, v16, v13
	v_div_fmas_f32 v7, v7, v10, v16
	v_div_fixup_f32 v29, v7, v29, v3
	v_div_scale_f32 v3, s[22:23], v28, v28, v1
	v_rcp_f32_e32 v7, v3
	v_pk_mul_f32 v[18:19], v[26:27], v[18:19] op_sel:[1,0] op_sel_hi:[0,1]
	v_pk_fma_f32 v[14:15], v[26:27], v[14:15], v[18:19]
	v_fma_f32 v10, -v3, v7, 1.0
	v_fmac_f32_e32 v7, v10, v7
	v_div_scale_f32 v10, vcc, v1, v28, v1
	v_mul_f32_e32 v13, v10, v7
	v_fma_f32 v16, -v3, v13, v10
	v_fmac_f32_e32 v13, v16, v7
	v_fma_f32 v3, -v3, v13, v10
	v_div_fmas_f32 v3, v3, v7, v13
	v_div_fixup_f32 v28, v3, v28, v1
	v_pk_fma_f32 v[14:15], v[6:7], v[22:23], v[14:15] op_sel_hi:[0,1,1]
	v_pk_mul_f32 v[14:15], v[28:29], v[14:15]
	v_lshlrev_b32_e32 v16, 16, v11
	v_cvt_pk_bf16_f32 v10, v14, v15
	v_lshlrev_b32_e32 v14, 16, v17
	v_and_b32_e32 v17, 0xffff0000, v17
	v_and_b32_e32 v15, 0xffff0000, v11
	v_pk_mul_f32 v[16:17], v[26:27], v[16:17] op_sel:[1,0] op_sel_hi:[0,1]
	v_lshlrev_b32_e32 v1, 16, v25
	v_pk_fma_f32 v[14:15], v[26:27], v[14:15], v[16:17]
	v_lshlrev_b32_e32 v16, 16, v21
	v_and_b32_e32 v17, 0xffff0000, v21
	v_and_b32_e32 v3, 0xffff0000, v25
	v_mul_f32_e32 v11, 0xbfb8aa3b, v1
	v_pk_fma_f32 v[6:7], v[6:7], v[16:17], v[14:15] op_sel_hi:[0,1,1]
	v_exp_f32_e32 v14, v11
	v_mul_f32_e32 v11, 0xbfb8aa3b, v3
	v_exp_f32_e32 v15, v11
	s_nop 0
	v_pk_add_f32 v[14:15], v[14:15], 1.0 op_sel_hi:[1,0]
	s_nop 0
	v_div_scale_f32 v11, s[22:23], v15, v15, v3
	v_rcp_f32_e32 v13, v11
	s_nop 0
	v_fma_f32 v16, -v11, v13, 1.0
	v_fmac_f32_e32 v13, v16, v13
	v_div_scale_f32 v16, vcc, v3, v15, v3
	v_mul_f32_e32 v17, v16, v13
	v_fma_f32 v18, -v11, v17, v16
	v_fmac_f32_e32 v17, v18, v13
	v_fma_f32 v11, -v11, v17, v16
	v_div_fmas_f32 v11, v11, v13, v17
	v_div_fixup_f32 v15, v11, v15, v3
	v_div_scale_f32 v3, s[22:23], v14, v14, v1
	v_rcp_f32_e32 v11, v3
	s_nop 0
	v_fma_f32 v13, -v3, v11, 1.0
	v_fmac_f32_e32 v11, v13, v11
	v_div_scale_f32 v13, vcc, v1, v14, v1
	v_mul_f32_e32 v16, v13, v11
	v_fma_f32 v17, -v3, v16, v13
	v_fmac_f32_e32 v16, v17, v11
	v_fma_f32 v3, -v3, v16, v13
	v_div_fmas_f32 v3, v3, v11, v16
	v_div_fixup_f32 v14, v3, v14, v1
	v_pk_mul_f32 v[6:7], v[14:15], v[6:7]
	v_cmp_lt_i32_e32 vcc, s0, v2
	v_cvt_pk_bf16_f32 v11, v6, v7
	s_or_b64 s[36:37], vcc, s[36:37]
	global_store_dwordx4 v[4:5], v[8:11], off
	s_andn2_b64 exec, exec, s[36:37]
	s_cbranch_execnz .LBB0_132

; #define LAS __attribute__((address_space(3)))
; DI void dil_store(const DilPre& P, bf16x8 (&qf)[4], ldsp lds, const bf16_t* proj, const float* rope, int item, int tid, int wid, int lane) {
;     const DilItem d = dil_decode(item);
;     const ldsp Kb = lds, Vb = lds + 256 * DIL_KS;
;     const int li = lane & 15, quad = lane >> 4;
;     const int tq = (128 * d.jb + 16 * wid + li) * d.r + d.ph;
;     float4 qcs[4], kcs[4];
;     {
;         const bf16_t* qsrc = proj + (d.rowbase + tq) * DIL_N + d.qcol + quad * 8;
; #pragma unroll
;         for (int ks = 0; ks < 4; ++ks) qf[ks] = *(const bf16x8*)(qsrc + ks * 32);
;         const float4* rp = (const float4*)(rope + (size_t)tq * 32 + 16 * (quad & 1));
; #pragma unroll
;         for (int jj = 0; jj < 4; ++jj) qcs[jj] = rp[jj];
;     }
;     const int prow = tid >> 1, pc = tid & 1, psp = d.s_k0 + prow;
;     u32x4 kp1 = (u32x4){0u, 0u, 0u, 0u}, kp2 = kp1;
;     {
;         const int tok = (psp >= 0 ? psp : 0) * d.r + d.ph;
;         const bf16_t* ksrc = proj + (d.rowbase + tok) * DIL_N + d.qcol + 768 + 8 * pc;
;         kp1 = *(const u32x4*)ksrc; kp2 = *(const u32x4*)(ksrc + 16);
;         const float4* rp = (const float4*)(rope + (size_t)tok * 32 + 16 * pc);
; #pragma unroll
;         for (int jj = 0; jj < 4; ++jj) kcs[jj] = rp[jj];
;     }
; #pragma unroll
;     for (int i = 0; i < 6; ++i) {
;         const int e = tid + i * 512, row = e / 12, ch = 4 + (e - row * 12), sp = d.s_k0 + row;
;         if (sp >= 0) *(LAS u32x4*)(Kb + row * DIL_KS + ch * 16) = P.kc[i];
;     }
.LBB0_331:
	s_ashr_i32 s19, s15, 4
	s_mul_hi_i32 s22, s19, 0x55555556
	s_lshr_b32 s23, s22, 31
	s_add_i32 s22, s22, s23
	s_mul_i32 s23, s22, 3
	s_sub_i32 s36, s19, s23
	s_mul_hi_i32 s23, s22, 0x2aaaaaab
	s_lshr_b32 s26, s23, 31
	s_add_i32 s23, s23, s26
	s_mul_i32 s23, s23, 6
	s_mul_hi_i32 s19, s19, 0x38e38e39
	s_lshr_b32 s14, s15, 8
	s_sub_i32 s58, s22, s23
	s_lshr_b32 s22, s19, 31
	s_ashr_i32 s19, s19, 2
	s_lshl_b32 s37, s36, 1
	s_add_i32 s14, s14, s15
	s_add_i32 s22, s19, s22
	s_lshr_b32 s19, 16, s37
	v_mov_b32_e32 v135, v32
	s_and_b32 s14, s14, 15
	s_sub_i32 s23, 4, s37
	s_add_i32 s19, s19, -1
	s_lshr_b32 s59, s14, s23
	v_readfirstlane_b32 s17, v135
	s_and_b32 s19, s19, s14
	s_ashr_i32 s23, s22, 31
	s_mul_i32 s14, s36, 0x900
	s_lshl_b32 s60, s58, 7
	s_lshl_b64 s[62:63], s[22:23], 11
	s_add_i32 s22, s60, s14
	s_ashr_i32 s14, s17, 2
	s_lshl_b32 s61, s19, 7
	s_and_b32 s65, s14, -16
	v_and_b32_e32 v136, 15, v135
	s_add_i32 s14, s65, s61
	v_or_b32_e32 v13, s14, v136
	v_lshlrev_b32_e32 v13, s37, v13
	v_add_u32_e32 v14, s59, v13
	v_ashrrev_i32_e32 v15, 31, v14
	v_lshl_add_u64 v[62:63], s[62:63], 0, v[14:15]
	v_lshlrev_b64 v[62:63], 14, v[62:63]
	s_ashr_i32 s23, s22, 31
	v_readlane_b32 s26, v254, 58
	v_lshl_add_u64 v[62:63], s[42:43], 0, v[62:63]
	s_lshl_b64 s[22:23], s[22:23], 1
	v_lshlrev_b64 v[14:15], 7, v[14:15]
	v_readlane_b32 s27, v254, 59
	v_and_b32_e32 v13, 16, v135
	v_lshl_add_u64 v[62:63], v[62:63], 0, s[22:23]
	v_and_b32_e32 v118, 48, v135
	v_mov_b32_e32 v119, v12
	v_lshl_add_u64 v[14:15], s[26:27], 0, v[14:15]
	v_lshlrev_b32_e32 v78, 2, v13
	v_mov_b32_e32 v79, v12
	v_lshl_add_u64 v[70:71], v[62:63], 0, v[118:119]
	v_lshl_add_u64 v[14:15], v[14:15], 0, v[78:79]
	s_add_i32 s14, s61, 0xffffff80
	v_ashrrev_i32_e32 v33, 1, v135
	global_load_dwordx4 v[74:77], v[70:71], off
	global_load_dwordx4 v[62:65], v[70:71], off offset:64
	global_load_dwordx4 v[66:69], v[70:71], off offset:128
	s_nop 0
	global_load_dwordx4 v[70:73], v[70:71], off offset:192
	s_nop 0
	global_load_dwordx4 v[78:81], v[14:15], off offset:48
	global_load_dwordx4 v[82:85], v[14:15], off offset:32
	global_load_dwordx4 v[86:89], v[14:15], off offset:16
	global_load_dwordx4 v[90:93], v[14:15], off
	v_add_u32_e32 v14, s14, v33
	v_cmp_lt_i32_e32 vcc, -1, v14
	v_and_b32_e32 v13, 1, v135
	s_sub_i32 s64, 0x7f, s61
	v_cndmask_b32_e32 v14, 0, v14, vcc
	v_lshlrev_b32_e32 v14, s37, v14
	v_add_u32_e32 v94, s59, v14
	v_ashrrev_i32_e32 v95, 31, v94
	v_lshl_add_u64 v[14:15], s[62:63], 0, v[94:95]
	v_lshlrev_b64 v[14:15], 14, v[14:15]
	v_lshl_add_u64 v[14:15], s[42:43], 0, v[14:15]
	v_lshl_add_u64 v[96:97], v[14:15], 0, s[22:23]
	v_lshlrev_b32_e32 v14, 4, v13
	v_mov_b32_e32 v15, v12
	v_lshl_add_u64 v[96:97], v[96:97], 0, v[14:15]
	v_lshlrev_b64 v[94:95], 7, v[94:95]
	global_load_dwordx4 v[98:101], v[96:97], off offset:1536
	global_load_dwordx4 v[102:105], v[96:97], off offset:1568
	v_lshl_add_u64 v[94:95], s[26:27], 0, v[94:95]
	v_lshlrev_b32_e32 v96, 6, v13
	v_mov_b32_e32 v97, v12
	v_lshl_add_u64 v[114:115], v[94:95], 0, v[96:97]
	global_load_dwordx4 v[94:97], v[114:115], off offset:48
	global_load_dwordx4 v[106:109], v[114:115], off offset:32
	global_load_dwordx4 v[110:113], v[114:115], off offset:16
	s_nop 0
	global_load_dwordx4 v[114:117], v[114:115], off
	v_mul_hi_i32 v13, v135, s68
	v_lshrrev_b32_e32 v15, 31, v13
	v_ashrrev_i32_e32 v13, 1, v13
	v_add_u32_e32 v139, v13, v15
	v_cmp_lt_i32_e64 s[38:39], s64, v139
	s_and_saveexec_b64 s[22:23], s[38:39]
	s_cbranch_execz .LBB0_333
	s_mov_b32 s14, 0xffffff4
	v_mul_lo_u32 v13, v139, s14
	s_movk_i32 s14, 0x110
	v_mul_lo_u32 v15, v139, s14
	v_add_lshl_u32 v13, v13, v135, 4
	v_add3_u32 v13, 0, v15, v13
	s_waitcnt vmcnt(14) lgkmcnt(0)
	ds_write_b128 v13, v[4:7] offset:64
.LBB0_333:
	s_or_b64 exec, exec, s[22:23]
	v_add_u32_e32 v13, 0x200, v135
	v_mul_hi_i32 v15, v13, s68
	v_lshrrev_b32_e32 v119, 31, v15
	v_ashrrev_i32_e32 v15, 1, v15
	v_add_u32_e32 v15, v15, v119
	v_cmp_lt_i32_e64 s[38:39], s64, v15
	s_and_saveexec_b64 s[22:23], s[38:39]
	s_cbranch_execz .LBB0_335
	s_mov_b32 s14, 0xffffff4
	v_mul_lo_u32 v119, v15, s14
	s_movk_i32 s14, 0x110
	v_mul_lo_u32 v120, v15, s14
	v_add_lshl_u32 v119, v119, v13, 4
	v_add3_u32 v119, 0, v120, v119
	s_waitcnt vmcnt(14)
	ds_write_b128 v119, v[0:3] offset:64
.LBB0_335:
	s_or_b64 exec, exec, s[22:23]
	v_add_u32_e32 v134, 0x400, v135
	v_mul_hi_i32 v119, v134, s68
	v_lshrrev_b32_e32 v120, 31, v119
	v_ashrrev_i32_e32 v119, 1, v119
	v_add_u32_e32 v138, v119, v120
	v_cmp_lt_i32_e64 s[38:39], s64, v138
	s_and_saveexec_b64 s[22:23], s[38:39]
	s_cbranch_execz .LBB0_337
	s_mov_b32 s14, 0xffffff4
	v_mul_lo_u32 v119, v138, s14
	s_movk_i32 s14, 0x110
	v_mul_lo_u32 v120, v138, s14
	v_add_lshl_u32 v119, v119, v134, 4
	v_add3_u32 v119, 0, v120, v119
	s_waitcnt vmcnt(14)
	ds_write_b128 v119, v[8:11] offset:64
; #define LAS __attribute__((address_space(3)))
; DI void dil_store(const DilPre& P, bf16x8 (&qf)[4], ldsp lds, const bf16_t* proj, const float* rope, int item, int tid, int wid, int lane) {
;     ...
; #pragma unroll
;     for (int i = 0; i < 6; ++i) {
;         const int e = tid + i * 512, row = e / 12, ch = 4 + (e - row * 12), sp = d.s_k0 + row;
;         if (sp >= 0) *(LAS u32x4*)(Kb + row * DIL_KS + ch * 16) = P.kc[i];
;     }
; #pragma unroll
;     for (int i = 0; i < 8; ++i) {
;         const int e = tid + i * 512, row = e >> 4, ch = e & 15, sp = d.s_k0 + row;
;         if (sp >= 0) *(LAS u32x4*)(Vb + row * DIL_KS + ch * 16) = P.vv[i];
;     }
.LBB0_337:
	s_or_b64 exec, exec, s[22:23]
	v_add_u32_e32 v132, 0x600, v135
	v_mul_hi_i32 v119, v132, s68
	v_lshrrev_b32_e32 v120, 31, v119
	v_ashrrev_i32_e32 v119, 1, v119
	v_add_u32_e32 v137, v119, v120
	v_cmp_lt_i32_e64 s[38:39], s64, v137
	s_and_saveexec_b64 s[22:23], s[38:39]
	s_cbranch_execz .LBB0_339
	s_mov_b32 s14, 0xffffff4
	v_mul_lo_u32 v119, v137, s14
	s_movk_i32 s14, 0x110
	v_mul_lo_u32 v120, v137, s14
	v_add_lshl_u32 v119, v119, v132, 4
	v_add3_u32 v119, 0, v120, v119
	s_waitcnt vmcnt(14)
	ds_write_b128 v119, v[16:19] offset:64
.LBB0_339:
	s_or_b64 exec, exec, s[22:23]
	v_add_u32_e32 v129, 0x800, v135
	v_mul_hi_i32 v119, v129, s68
	v_lshrrev_b32_e32 v120, 31, v119
	v_ashrrev_i32_e32 v119, 1, v119
	v_add_u32_e32 v133, v119, v120
	v_cmp_lt_i32_e64 s[38:39], s64, v133
	s_and_saveexec_b64 s[22:23], s[38:39]
	s_cbranch_execz .LBB0_341
	s_mov_b32 s14, 0xffffff4
	v_mul_lo_u32 v119, v133, s14
	s_movk_i32 s14, 0x110
	v_mul_lo_u32 v120, v133, s14
	v_add_lshl_u32 v119, v119, v129, 4
	v_add3_u32 v119, 0, v120, v119
	s_waitcnt vmcnt(14)
	ds_write_b128 v119, v[20:23] offset:64
.LBB0_341:
	s_or_b64 exec, exec, s[22:23]
	v_add_u32_e32 v128, 0xa00, v135
	v_mul_hi_i32 v119, v128, s68
	v_lshrrev_b32_e32 v120, 31, v119
	v_ashrrev_i32_e32 v119, 1, v119
	v_add_u32_e32 v130, v119, v120
	v_cmp_lt_i32_e64 s[38:39], s64, v130
	s_and_saveexec_b64 s[22:23], s[38:39]
	s_cbranch_execz .LBB0_343
	s_mov_b32 s14, 0xffffff4
	v_mul_lo_u32 v119, v130, s14
	s_movk_i32 s14, 0x110
	v_mul_lo_u32 v120, v130, s14
	v_add_lshl_u32 v119, v119, v128, 4
	v_add3_u32 v119, 0, v120, v119
	s_waitcnt vmcnt(14)
	ds_write_b128 v119, v[24:27] offset:64
.LBB0_343:
	s_or_b64 exec, exec, s[22:23]
	v_lshlrev_b32_e32 v119, 4, v135
	v_and_b32_e32 v119, 0xf0, v119
	v_readlane_b32 s14, v254, 46
	v_ashrrev_i32_e32 v131, 4, v135
	v_cmp_lt_i32_e64 s[38:39], s64, v131
	v_add_u32_e32 v120, s14, v119
	s_and_saveexec_b64 s[22:23], s[38:39]
	s_cbranch_execz .LBB0_345
	s_movk_i32 s14, 0x110
	v_mad_u64_u32 v[122:123], s[26:27], v131, s14, v[120:121]
	s_waitcnt vmcnt(14)
	ds_write_b128 v122, v[28:31]
.LBB0_345:
	s_or_b64 exec, exec, s[22:23]
	v_ashrrev_i32_e32 v127, 4, v13
	v_cmp_lt_i32_e64 s[38:39], s64, v127
	s_and_saveexec_b64 s[22:23], s[38:39]
	s_cbranch_execz .LBB0_347
	s_movk_i32 s14, 0x110
	v_mad_u64_u32 v[122:123], s[26:27], v127, s14, v[120:121]
	s_waitcnt vmcnt(14)
	ds_write_b128 v122, v[34:37]
.LBB0_347:
	s_or_b64 exec, exec, s[22:23]
	v_ashrrev_i32_e32 v126, 4, v134
	v_cmp_lt_i32_e64 s[38:39], s64, v126
	s_and_saveexec_b64 s[22:23], s[38:39]
	s_cbranch_execz .LBB0_349
	s_movk_i32 s14, 0x110
	v_mad_u64_u32 v[122:123], s[26:27], v126, s14, v[120:121]
	s_waitcnt vmcnt(14) lgkmcnt(0)
	ds_write_b128 v122, v[38:41]
.LBB0_349:
	s_or_b64 exec, exec, s[22:23]
	v_ashrrev_i32_e32 v125, 4, v132
	v_cmp_lt_i32_e64 s[38:39], s64, v125
	s_and_saveexec_b64 s[22:23], s[38:39]
	s_cbranch_execz .LBB0_351
	s_movk_i32 s14, 0x110
	v_mad_u64_u32 v[122:123], s[26:27], v125, s14, v[120:121]
	s_waitcnt vmcnt(14) lgkmcnt(0)
	ds_write_b128 v122, v[42:45]
.LBB0_351:
	s_or_b64 exec, exec, s[22:23]
	v_ashrrev_i32_e32 v124, 4, v129
	v_cmp_lt_i32_e64 s[38:39], s64, v124
	s_and_saveexec_b64 s[22:23], s[38:39]
	s_cbranch_execz .LBB0_353
	s_movk_i32 s14, 0x110
	v_mad_u64_u32 v[122:123], s[26:27], v124, s14, v[120:121]
	s_waitcnt vmcnt(14)
	ds_write_b128 v122, v[46:49]
.LBB0_353:
	s_or_b64 exec, exec, s[22:23]
	v_ashrrev_i32_e32 v123, 4, v128
	v_cmp_lt_i32_e64 s[38:39], s64, v123
	s_and_saveexec_b64 s[22:23], s[38:39]
	s_cbranch_execz .LBB0_355
	s_movk_i32 s14, 0x110
	v_mad_u64_u32 v[140:141], s[26:27], v123, s14, v[120:121]
	s_waitcnt vmcnt(14)
	ds_write_b128 v140, v[50:53]
.LBB0_355:
	s_or_b64 exec, exec, s[22:23]
	v_add_u32_e32 v119, 0xc00, v135
	v_ashrrev_i32_e32 v122, 4, v119
	v_cmp_lt_i32_e64 s[38:39], s64, v122
	s_and_saveexec_b64 s[22:23], s[38:39]
	s_cbranch_execz .LBB0_357
	s_movk_i32 s14, 0x110
	v_mad_u64_u32 v[140:141], s[26:27], v122, s14, v[120:121]
	s_waitcnt vmcnt(14)
	ds_write_b128 v140, v[54:57]
.LBB0_357:
	s_or_b64 exec, exec, s[22:23]
	v_add_u32_e32 v119, 0xe00, v135
	v_ashrrev_i32_e32 v121, 4, v119
	v_cmp_lt_i32_e64 s[38:39], s64, v121
	s_and_saveexec_b64 s[22:23], s[38:39]
	s_cbranch_execz .LBB0_359
	s_movk_i32 s14, 0x110
	v_mad_u64_u32 v[140:141], s[26:27], v121, s14, v[120:121]
	s_waitcnt vmcnt(14)
	ds_write_b128 v140, v[58:61]

; DI void dil_combine(const bf16_t* og, const float* lse, const bf16_t* proj, bf16_t* br, int b0, int u0, int u1, int ustride) {
;     for (int u = u0; u < u1; u += ustride) {
;         const int row = u / 96, ch = u - row * 96, head = ch >> 4;
;         const float l0 = lse[(size_t)row * 18 + head], l1 = lse[(size_t)row * 18 + 6 + head], l2 = lse[(size_t)row * 18 + 12 + head];
;         const float m = fmaxf(l0, fmaxf(l1, l2));
;         float e0 = __expf(l0 - m), e1 = __expf(l1 - m), e2 = __expf(l2 - m);
;         const float is = 1.0f / (e0 + e1 + e2); e0 *= is; e1 *= is; e2 *= is;
;         const bf16_t* ob = og + (size_t)row * 2304 + ch * 8;
;         const u32x4 a = *(const u32x4*)ob, bq = *(const u32x4*)(ob + 768), c = *(const u32x4*)(ob + 1536);
;         const u32x4 gv = *(const u32x4*)(proj + (size_t)row * DIL_N + DB_GATE + ch * 8);
.LBB0_433:
	v_mul_hi_i32 v13, v14, s68
	v_lshrrev_b32_e32 v15, 31, v13
	v_ashrrev_i32_e32 v13, 4, v13
	v_add_u32_e32 v64, v13, v15
	v_mad_u64_u32 v[66:67], s[22:23], v64, s19, v[14:15]
	v_ashrrev_i32_e32 v66, 4, v66
	v_mov_b64_e32 v[68:69], s[44:45]
	v_ashrrev_i32_e32 v67, 31, v66
	v_mad_i64_i32 v[68:69], s[22:23], v64, s34, v[68:69]
	v_lshl_add_u64 v[66:67], v[66:67], 2, v[68:69]
	global_load_dword v13, v[66:67], off
	global_load_dword v15, v[66:67], off offset:24
	global_load_dword v33, v[66:67], off offset:48
	v_ashrrev_i32_e32 v65, 31, v64
	v_lshlrev_b64 v[80:81], 14, v[64:65]
	v_lshl_add_u64 v[80:81], s[52:53], 0, v[80:81]
	v_add_u32_e32 v14, 0x200, v14
	v_mad_u64_u32 v[70:71], s[22:23], v64, s17, v[62:63]
	v_ashrrev_i32_e32 v71, 31, v70
	v_lshlrev_b64 v[88:89], 1, v[70:71]
	v_mov_b64_e32 v[68:69], s[40:41]
	v_lshl_add_u64 v[80:81], v[80:81], 0, v[88:89]
	v_mad_i64_i32 v[68:69], s[22:23], v64, s35, v[68:69]
	v_add_co_u32_e32 v80, vcc, s73, v80
	v_lshl_add_u64 v[76:77], v[68:69], 0, v[88:89]
	s_nop 0
	v_addc_co_u32_e32 v81, vcc, 0, v81, vcc
	global_load_dwordx4 v[68:71], v[76:77], off
	global_load_dwordx4 v[72:75], v[76:77], off offset:1536
	s_nop 0
	global_load_dwordx4 v[76:79], v[76:77], off offset:3072
	global_load_dwordx4 v[80:83], v[80:81], off offset:2048
	s_waitcnt vmcnt(4)
	v_max3_f32 v63, v13, v15, v33
	v_sub_f32_e32 v13, v13, v63
	v_mul_f32_e32 v13, 0x3fb8aa3b, v13
	v_exp_f32_e32 v85, v13
	v_sub_f32_e32 v13, v15, v63
	v_mul_f32_e32 v13, 0x3fb8aa3b, v13
	v_exp_f32_e32 v84, v13
	v_sub_f32_e32 v13, v33, v63
	v_mul_f32_e32 v13, 0x3fb8aa3b, v13
	v_exp_f32_e32 v13, v13
	v_add_f32_e32 v15, v85, v84
	v_add_f32_e32 v15, v13, v15
	v_div_scale_f32 v33, s[22:23], v15, v15, 1.0
	v_rcp_f32_e32 v63, v33
	s_nop 0
	v_fma_f32 v66, -v33, v63, 1.0
	v_fmac_f32_e32 v63, v66, v63
	v_div_scale_f32 v66, vcc, 1.0, v15, 1.0
	v_mul_f32_e32 v67, v66, v63
	v_fma_f32 v90, -v33, v67, v66
	v_fmac_f32_e32 v67, v90, v63
	v_fma_f32 v33, -v33, v67, v66
	s_nop 1
	v_div_fmas_f32 v33, v33, v63, v67
	v_div_fixup_f32 v86, v33, v15, 1.0
	v_mul_f32_e32 v66, v13, v86
	v_pk_mul_f32 v[84:85], v[84:85], v[86:87] op_sel_hi:[1,0]
	v_lshlrev_b64 v[64:65], 11, v[64:65]
	v_lshl_add_u64 v[64:65], s[54:55], 0, v[64:65]
	v_lshl_add_u64 v[64:65], v[64:65], 0, v[88:89]
	v_add_u32_e32 v62, 0x1000, v62
	s_waitcnt vmcnt(3)
	v_and_b32_e32 v87, 0xffff0000, v68
	v_lshlrev_b32_e32 v90, 16, v68
	s_waitcnt vmcnt(2)
	v_lshlrev_b32_e32 v86, 16, v72
	v_and_b32_e32 v91, 0xffff0000, v72
	s_waitcnt vmcnt(0)
; DI unsigned cvt_pk_bf16(float lo, float hi) { const f32x2_t v = {lo, hi}; const bf16v2_t b = __builtin_convertvector(v, bf16v2_t); return __builtin_bit_cast(unsigned, b); }
; DI float bf_lo(unsigned u) { return __uint_as_float(u << 16); }
; DI float bf_hi(unsigned u) { return __uint_as_float(u & 0xffff0000u); }
; DI float silu_f(float x) { return x / (1.0f + __expf(-x)); }
; DI void dil_combine(const bf16_t* og, const float* lse, const bf16_t* proj, bf16_t* br, int b0, int u0, int u1, int ustride) {
;     ...
;         u32x4 w;
; #pragma unroll
;         for (int e = 0; e < 4; ++e) {
;             const float vlo = e0 * bf_lo(a[e]) + e1 * bf_lo(bq[e]) + e2 * bf_lo(c[e]);
;             const float vhi = e0 * bf_hi(a[e]) + e1 * bf_hi(bq[e]) + e2 * bf_hi(c[e]);
;             w[e] = cvt_pk_bf16(vlo * silu_f(bf_lo(gv[e])), vhi * silu_f(bf_hi(gv[e])));
;         }
;         *(u32x4*)(br + ((size_t)b0 * SEQ + row) * 1024 + ch * 8) = w;
	v_lshlrev_b32_e32 v13, 16, v80
	v_and_b32_e32 v15, 0xffff0000, v80
	v_mul_f32_e32 v33, 0xbfb8aa3b, v13
	v_exp_f32_e32 v94, v33
	v_mul_f32_e32 v33, 0xbfb8aa3b, v15
	v_exp_f32_e32 v95, v33
	v_pk_mul_f32 v[90:91], v[84:85], v[90:91] op_sel:[1,0] op_sel_hi:[0,1]
	v_lshlrev_b32_e32 v92, 16, v76
	v_and_b32_e32 v93, 0xffff0000, v76
	v_pk_add_f32 v[94:95], v[94:95], 1.0 op_sel_hi:[1,0]
	v_pk_fma_f32 v[86:87], v[84:85], v[86:87], v[90:91]
	v_div_scale_f32 v33, s[22:23], v95, v95, v15
	v_rcp_f32_e32 v63, v33
	v_lshlrev_b32_e32 v76, 16, v77
	v_and_b32_e32 v77, 0xffff0000, v77
	v_fma_f32 v67, -v33, v63, 1.0
	v_fmac_f32_e32 v63, v67, v63
	v_div_scale_f32 v67, vcc, v15, v95, v15
	v_mul_f32_e32 v68, v67, v63
	v_fma_f32 v72, -v33, v68, v67
	v_fmac_f32_e32 v68, v72, v63
	v_fma_f32 v33, -v33, v68, v67
	v_div_fmas_f32 v33, v33, v63, v68
	v_div_fixup_f32 v95, v33, v95, v15
	v_div_scale_f32 v15, s[22:23], v94, v94, v13
	v_rcp_f32_e32 v33, v15
	v_lshlrev_b32_e32 v72, 16, v69
	v_fma_f32 v63, -v15, v33, 1.0
	v_fmac_f32_e32 v33, v63, v33
	v_div_scale_f32 v63, vcc, v13, v94, v13
	v_mul_f32_e32 v67, v63, v33
	v_fma_f32 v68, -v15, v67, v63
	v_fmac_f32_e32 v67, v68, v33
	v_fma_f32 v15, -v15, v67, v63
	v_div_fmas_f32 v15, v15, v33, v67
	v_div_fixup_f32 v94, v15, v94, v13
	v_lshlrev_b32_e32 v13, 16, v81
	v_and_b32_e32 v15, 0xffff0000, v81
	v_mul_f32_e32 v33, 0xbfb8aa3b, v13
	v_exp_f32_e32 v80, v33
	v_mul_f32_e32 v33, 0xbfb8aa3b, v15
	v_exp_f32_e32 v81, v33
	v_pk_fma_f32 v[86:87], v[66:67], v[92:93], v[86:87] op_sel_hi:[0,1,1]
	v_pk_mul_f32 v[86:87], v[94:95], v[86:87]
	v_pk_add_f32 v[80:81], v[80:81], 1.0 op_sel_hi:[1,0]
	s_nop 0
	v_div_scale_f32 v33, s[22:23], v81, v81, v15
	v_rcp_f32_e32 v63, v33
	v_cvt_pk_bf16_f32 v68, v86, v87
	v_and_b32_e32 v87, 0xffff0000, v69
	v_lshlrev_b32_e32 v86, 16, v73
	v_fma_f32 v67, -v33, v63, 1.0
	v_fmac_f32_e32 v63, v67, v63
	v_div_scale_f32 v67, vcc, v15, v81, v15
	v_mul_f32_e32 v69, v67, v63
	v_fma_f32 v90, -v33, v69, v67
	v_fmac_f32_e32 v69, v90, v63
	v_fma_f32 v33, -v33, v69, v67
	v_div_fmas_f32 v33, v33, v63, v69
	v_div_fixup_f32 v81, v33, v81, v15
	v_div_scale_f32 v15, s[22:23], v80, v80, v13
	v_rcp_f32_e32 v33, v15
	v_and_b32_e32 v73, 0xffff0000, v73
	v_pk_mul_f32 v[72:73], v[84:85], v[72:73] op_sel:[1,0] op_sel_hi:[0,1]
	v_pk_fma_f32 v[72:73], v[84:85], v[86:87], v[72:73]
	v_fma_f32 v63, -v15, v33, 1.0
	v_fmac_f32_e32 v33, v63, v33
	v_div_scale_f32 v63, vcc, v13, v80, v13
	v_mul_f32_e32 v67, v63, v33
	v_fma_f32 v69, -v15, v67, v63
	v_fmac_f32_e32 v67, v69, v33
	v_fma_f32 v15, -v15, v67, v63
	v_div_fmas_f32 v15, v15, v33, v67
	v_div_fixup_f32 v80, v15, v80, v13
	v_lshlrev_b32_e32 v13, 16, v82
	v_and_b32_e32 v15, 0xffff0000, v82
	v_mul_f32_e32 v33, 0xbfb8aa3b, v13
	v_exp_f32_e32 v86, v33
	v_mul_f32_e32 v33, 0xbfb8aa3b, v15
	v_exp_f32_e32 v87, v33
	v_pk_fma_f32 v[72:73], v[66:67], v[76:77], v[72:73] op_sel_hi:[0,1,1]
	v_pk_mul_f32 v[72:73], v[80:81], v[72:73]
	v_lshlrev_b32_e32 v76, 16, v70
	v_pk_add_f32 v[86:87], v[86:87], 1.0 op_sel_hi:[1,0]
	v_cvt_pk_bf16_f32 v69, v72, v73
	v_div_scale_f32 v33, s[22:23], v87, v87, v15
	v_rcp_f32_e32 v63, v33
	v_and_b32_e32 v73, 0xffff0000, v70
	v_lshlrev_b32_e32 v72, 16, v74
	v_and_b32_e32 v77, 0xffff0000, v74
	v_fma_f32 v67, -v33, v63, 1.0
	v_fmac_f32_e32 v63, v67, v63
	v_div_scale_f32 v67, vcc, v15, v87, v15
	v_mul_f32_e32 v70, v67, v63
	v_fma_f32 v74, -v33, v70, v67
	v_fmac_f32_e32 v70, v74, v63
	v_fma_f32 v33, -v33, v70, v67
	v_div_fmas_f32 v33, v33, v63, v70
	v_div_fixup_f32 v87, v33, v87, v15
	v_div_scale_f32 v15, s[22:23], v86, v86, v13
	v_rcp_f32_e32 v33, v15
	v_pk_mul_f32 v[76:77], v[84:85], v[76:77] op_sel:[1,0] op_sel_hi:[0,1]
	v_lshlrev_b32_e32 v80, 16, v78
	v_and_b32_e32 v81, 0xffff0000, v78
	v_fma_f32 v63, -v15, v33, 1.0
	v_fmac_f32_e32 v33, v63, v33
	v_div_scale_f32 v63, vcc, v13, v86, v13
	v_mul_f32_e32 v67, v63, v33
	v_fma_f32 v70, -v15, v67, v63
	v_fmac_f32_e32 v67, v70, v33
	v_fma_f32 v15, -v15, v67, v63
	v_div_fmas_f32 v15, v15, v33, v67
	v_pk_fma_f32 v[72:73], v[84:85], v[72:73], v[76:77]
	v_div_fixup_f32 v86, v15, v86, v13
	v_pk_fma_f32 v[72:73], v[66:67], v[80:81], v[72:73] op_sel_hi:[0,1,1]
	v_pk_mul_f32 v[72:73], v[86:87], v[72:73]
	v_lshlrev_b32_e32 v74, 16, v71
	v_cvt_pk_bf16_f32 v70, v72, v73
	v_lshlrev_b32_e32 v72, 16, v75
	v_and_b32_e32 v75, 0xffff0000, v75
	v_and_b32_e32 v73, 0xffff0000, v71
	v_pk_mul_f32 v[74:75], v[84:85], v[74:75] op_sel:[1,0] op_sel_hi:[0,1]
	v_lshlrev_b32_e32 v13, 16, v83
	v_pk_fma_f32 v[72:73], v[84:85], v[72:73], v[74:75]
	v_lshlrev_b32_e32 v74, 16, v79
	v_and_b32_e32 v75, 0xffff0000, v79
	v_and_b32_e32 v15, 0xffff0000, v83
	v_mul_f32_e32 v33, 0xbfb8aa3b, v13
	v_pk_fma_f32 v[66:67], v[66:67], v[74:75], v[72:73] op_sel_hi:[0,1,1]
	v_exp_f32_e32 v72, v33
	v_mul_f32_e32 v33, 0xbfb8aa3b, v15
	v_exp_f32_e32 v73, v33
	s_nop 0
	v_pk_add_f32 v[72:73], v[72:73], 1.0 op_sel_hi:[1,0]
	s_nop 0
	v_div_scale_f32 v33, s[22:23], v73, v73, v15
	v_rcp_f32_e32 v63, v33
	s_nop 0
	v_fma_f32 v71, -v33, v63, 1.0
	v_fmac_f32_e32 v63, v71, v63
	v_div_scale_f32 v71, vcc, v15, v73, v15
	v_mul_f32_e32 v74, v71, v63
	v_fma_f32 v75, -v33, v74, v71
	v_fmac_f32_e32 v74, v75, v63
	v_fma_f32 v33, -v33, v74, v71
	v_div_fmas_f32 v33, v33, v63, v74
	v_div_fixup_f32 v73, v33, v73, v15
	v_div_scale_f32 v15, s[22:23], v72, v72, v13
	v_rcp_f32_e32 v33, v15
	s_nop 0
	v_fma_f32 v63, -v15, v33, 1.0
	v_fmac_f32_e32 v33, v63, v33
	v_div_scale_f32 v63, vcc, v13, v72, v13
	v_mul_f32_e32 v71, v63, v33
	v_fma_f32 v74, -v15, v71, v63
	v_fmac_f32_e32 v71, v74, v33
	v_fma_f32 v15, -v15, v71, v63
	v_div_fmas_f32 v15, v15, v33, v71
	v_div_fixup_f32 v72, v15, v72, v13
	v_pk_mul_f32 v[66:67], v[72:73], v[66:67]
	v_cmp_le_i32_e32 vcc, s15, v14
	v_cvt_pk_bf16_f32 v71, v66, v67
	s_or_b64 s[30:31], vcc, s[30:31]
	global_store_dwordx4 v[64:65], v[68:71], off
	s_andn2_b64 exec, exec, s[30:31]
	s_cbranch_execnz .LBB0_433
	s_branch .LBB0_329

; #define LAS __attribute__((address_space(3)))
; DI void mem_attn_item(ldsp lds, const bf16_t* proj, int ldp, int qmcol, int gatecol, const bf16_t* kv, bf16_t* branch, int b0, int item, int tid, int wid, int lane, const bool stage = true) {
;     ...
;     if (stage)
; #pragma unroll
;     for (int i = 0; i < 4; ++i) {
;         const int e = tid + i * 512, row = e >> 3, ch = e & 7;
;         const u32x4 kx = *(const u32x4*)(kvb + (size_t)row * 2048 + ch * 8);
;         const u32x4 vx = *(const u32x4*)(kvb + (size_t)row * 2048 + 256 + ch * 8);
;         *(LAS u32x4*)(Kb + row * KS + ch * 16) = kx;
;         *(LAS u32x4*)(Vb + row * KS + ch * 16) = vx;
;     }
.LBB0_445:
	s_xor_b64 s[40:41], s[22:23], -1
	s_and_b64 vcc, exec, s[40:41]
	s_cbranch_vccnz .LBB0_444
	global_load_dwordx4 v[34:37], v[74:75], off
	global_load_dwordx4 v[38:41], v[74:75], off offset:512
	global_load_dwordx4 v[42:45], v[76:77], off
	global_load_dwordx4 v[46:49], v[76:77], off offset:512
	global_load_dwordx4 v[50:53], v[78:79], off
	global_load_dwordx4 v[54:57], v[78:79], off offset:512
	global_load_dwordx4 v[58:61], v[80:81], off
	global_load_dwordx4 v[62:65], v[80:81], off offset:512
	s_waitcnt vmcnt(7)
	ds_write_b128 v31, v[34:37]
	s_waitcnt vmcnt(6)
	ds_write_b128 v31, v[38:41] offset:36864
	s_waitcnt vmcnt(5)
	ds_write_b128 v99, v[42:45]
	s_waitcnt vmcnt(4)
	ds_write_b128 v99, v[46:49] offset:36864
	s_waitcnt vmcnt(3)
	ds_write_b128 v100, v[50:53]
	s_waitcnt vmcnt(2)
	ds_write_b128 v100, v[54:57] offset:36864
	s_waitcnt vmcnt(1)
	ds_write_b128 v101, v[58:61]
	s_waitcnt vmcnt(0)
	ds_write_b128 v101, v[62:65] offset:36864
	s_branch .LBB0_444

; #define LAS __attribute__((address_space(3)))
; DI void mem_attn_item(ldsp lds, const bf16_t* proj, int ldp, int qmcol, int gatecol, const bf16_t* kv, bf16_t* branch, int b0, int item, int tid, int wid, int lane, const bool stage = true) {
;     ...
;     if (stage)
; #pragma unroll
;     for (int i = 0; i < 4; ++i) {
;         const int e = tid + i * 512, row = e >> 3, ch = e & 7;
;         const u32x4 kx = *(const u32x4*)(kvb + (size_t)row * 2048 + ch * 8);
;         const u32x4 vx = *(const u32x4*)(kvb + (size_t)row * 2048 + 256 + ch * 8);
;         *(LAS u32x4*)(Kb + row * KS + ch * 16) = kx;
;         *(LAS u32x4*)(Vb + row * KS + ch * 16) = vx;
;     }
.LBB0_512:
	s_cmp_lg_u32 s14, 0
	s_mov_b64 s[26:27], 0x1420
	s_cbranch_scc1 .LBB0_511
	global_load_dwordx4 v[34:37], v[30:31], off
	global_load_dwordx4 v[38:41], v[30:31], off offset:512
	global_load_dwordx4 v[42:45], v[74:75], off
	global_load_dwordx4 v[46:49], v[74:75], off offset:512
	global_load_dwordx4 v[50:53], v[76:77], off
	global_load_dwordx4 v[54:57], v[76:77], off offset:512
	global_load_dwordx4 v[58:61], v[78:79], off
	global_load_dwordx4 v[62:65], v[78:79], off offset:512
	s_waitcnt vmcnt(7)
	ds_write_b128 v99, v[34:37]
	s_waitcnt vmcnt(6)
	ds_write_b128 v99, v[38:41] offset:36864
	s_waitcnt vmcnt(5)
	ds_write_b128 v100, v[42:45]
	s_waitcnt vmcnt(4)
	ds_write_b128 v100, v[46:49] offset:36864
	s_waitcnt vmcnt(3)
	ds_write_b128 v101, v[50:53]
	s_waitcnt vmcnt(2)
	ds_write_b128 v101, v[54:57] offset:36864
	s_waitcnt vmcnt(1)
	ds_write_b128 v102, v[58:61]
	s_waitcnt vmcnt(0)
	ds_write_b128 v102, v[62:65] offset:36864
	s_branch .LBB0_511
